# S5 scan: plain v_pk_mul/add_f32 split into scalar pairs (76 sites) on top of the cvt_pk scan variant
# baseline (speedup 1.0000x reference)
; __device__ __forceinline__ void sincos_rev(float rev, float& s, float& c) { const float f = rev - floorf(rev); s = __builtin_amdgcn_sinf(f); c = __builtin_amdgcn_cosf(f); }
; __global__ void __launch_bounds__(NWAVES * 64, 2) mega_fwd(Args args) {
;     ...
;             const float lr = args.in[10][(dir * 32 + g) * 64 + p], li = args.in[11][(dir * 32 + g) * 64 + p], delta = expf(args.in[12][dir * 32 + g]);
;             const float mag = expf(16.0f * delta * lr); float sn, cs; { const double rev = 16.0 * (double)delta * (double)li * 0.15915494309189535; sincos_rev((float)(rev - floor(rev)), sn, cs); }
;             const float ar = mag * cs, ai = mag * sn;
;             const float* Eb = EB + ((size_t)(g * 1024 + b * 512)) * 256 + dir * 128 + p;
;             bf16* Ab = AUG + ((size_t)(g * 1024 + b * 512)) * 512 + 256 + dir * 128 + p;
;             float er[64], ei[64];
; #pragma unroll
;             for (int q = 0; q < 64; ++q) { const int sidx = seg * 64 + q, c = dir ? 511 - sidx : sidx; er[q] = Eb[(size_t)c * 256]; ei[q] = Eb[(size_t)c * 256 + 64]; }
.LBB0_679:
	s_lshl_b32 s1, s0, 5
	v_readlane_b32 s2, v252, 28
	v_readlane_b32 s3, v252, 29
	s_add_i32 s2, s1, s2
	v_lshl_or_b32 v8, s2, 6, v94
	v_readlane_b32 s12, v251, 1
	s_ashr_i32 s3, s2, 31
	v_ashrrev_i32_e32 v9, 31, v8
	v_readlane_b32 s20, v251, 9
	s_lshl_b64 s[2:3], s[2:3], 2
	v_lshlrev_b64 v[8:9], 2, v[8:9]
	v_readlane_b32 s16, v251, 5
	v_readlane_b32 s17, v251, 6
	v_readlane_b32 s18, v251, 7
	v_readlane_b32 s19, v251, 8
	v_readlane_b32 s21, v251, 10
	s_add_u32 s2, s20, s2
	v_lshl_add_u64 v[10:11], s[16:17], 0, v[8:9]
	v_lshl_add_u64 v[8:9], s[18:19], 0, v[8:9]
	s_addc_u32 s3, s21, s3
	global_load_dword v3, v[10:11], off
	s_mov_b32 s1, 0x3fb8aa3b
	global_load_dword v10, v[8:9], off
	s_lshl_b32 s10, s0, 7
	global_load_dword v8, v2, s[2:3]
	s_mov_b32 s2, 0xc2ce8ed0
	s_mov_b32 s3, 0x42b17218
	v_readlane_b32 s26, v251, 15
	v_readlane_b32 s27, v251, 16
	v_readlane_b32 s22, v251, 11
	v_readlane_b32 s23, v251, 12
	v_readlane_b32 s24, v251, 13
	v_readlane_b32 s25, v251, 14
	v_readlane_b32 s14, v251, 3
	v_readlane_b32 s15, v251, 4
	v_readlane_b32 s13, v251, 2
	s_mov_b32 s67, s88
	s_waitcnt vmcnt(0)
	v_mul_f32_e32 v9, 0x3fb8aa3b, v8
	v_fma_f32 v11, v8, s1, -v9
	v_rndne_f32_e32 v12, v9
	v_fmac_f32_e32 v11, 0x32a5705f, v8
	v_sub_f32_e32 v9, v9, v12
	v_add_f32_e32 v9, v9, v11
	v_exp_f32_e32 v9, v9
	v_cvt_i32_f32_e32 v11, v12
	v_cmp_ngt_f32_e32 vcc, s2, v8
	v_ldexp_f32 v9, v9, v11
	s_nop 0
	v_cndmask_b32_e32 v9, 0, v9, vcc
	v_cmp_nlt_f32_e32 vcc, s3, v8
	s_nop 1
	v_cndmask_b32_e32 v8, v96, v9, vcc
	v_mul_f32_e32 v9, 0x41800000, v8
	v_mul_f32_e32 v3, v3, v9
	v_mul_f32_e32 v9, 0x3fb8aa3b, v3
	v_fma_f32 v11, v3, s1, -v9
	v_rndne_f32_e32 v12, v9
	v_fmac_f32_e32 v11, 0x32a5705f, v3
	v_sub_f32_e32 v9, v9, v12
	v_add_f32_e32 v9, v9, v11
	v_exp_f32_e32 v9, v9
	v_cvt_i32_f32_e32 v11, v12
	v_cmp_ngt_f32_e32 vcc, s2, v3
	s_and_b64 s[0:1], s[40:41], exec
	v_readlane_b32 s0, v254, 40
	v_ldexp_f32 v9, v9, v11
	v_cndmask_b32_e32 v9, 0, v9, vcc
	v_cmp_nlt_f32_e32 vcc, s3, v3
	v_cvt_f64_f32_e32 v[10:11], v10
	s_mov_b32 s2, 0x6dc9c883
	v_cndmask_b32_e32 v86, v96, v9, vcc
	v_cvt_f64_f32_e32 v[8:9], v8
	v_ldexp_f64 v[8:9], v[8:9], 4
	v_mul_f64 v[8:9], v[8:9], v[10:11]
	s_mov_b32 s3, 0x3fc45f30
	v_mul_f64 v[10:11], v[8:9], s[2:3]
	v_floor_f64_e32 v[10:11], v[10:11]
	v_fma_f64 v[8:9], v[8:9], s[2:3], -v[10:11]
	v_readlane_b32 s1, v252, 45
	v_cvt_f32_f64_e32 v3, v[8:9]
	s_cselect_b32 s64, s0, s1
	v_floor_f32_e32 v8, v3
	s_ashr_i32 s65, s64, 31
	v_sub_f32_e32 v3, v3, v8
	v_lshl_add_u64 v[8:9], s[10:11], 2, v[4:5]
	s_lshl_b64 s[0:1], s[64:65], 10
	v_lshl_add_u64 v[10:11], v[8:9], 0, s[0:1]
	s_and_b64 s[0:1], s[40:41], exec
	v_readlane_b32 s0, v252, 46
	v_readlane_b32 s1, v252, 47
	s_cselect_b32 s62, s0, s1
	s_ashr_i32 s63, s62, 31
	s_lshl_b64 s[0:1], s[62:63], 10
	global_load_dword v147, v[10:11], off
	global_load_dword v145, v[10:11], off offset:256
	v_lshl_add_u64 v[10:11], v[8:9], 0, s[0:1]
	s_and_b64 s[0:1], s[40:41], exec
	v_readlane_b32 s0, v252, 48
	v_readlane_b32 s1, v252, 49
	s_cselect_b32 s38, s0, s1
	s_ashr_i32 s39, s38, 31
	s_lshl_b64 s[0:1], s[38:39], 10
	global_load_dword v82, v[10:11], off
	global_load_dword v83, v[10:11], off offset:256
	v_lshl_add_u64 v[10:11], v[8:9], 0, s[0:1]
	s_and_b64 s[0:1], s[40:41], exec
	v_readlane_b32 s0, v252, 50
	v_readlane_b32 s1, v252, 51
	s_cselect_b32 s4, s0, s1
	s_ashr_i32 s5, s4, 31
	s_lshl_b64 s[0:1], s[4:5], 10
	global_load_dword v143, v[10:11], off
	global_load_dword v141, v[10:11], off offset:256
	v_lshl_add_u64 v[10:11], v[8:9], 0, s[0:1]
	s_and_b64 s[0:1], s[40:41], exec
	v_readlane_b32 s0, v252, 52
	v_readlane_b32 s1, v252, 53
	s_cselect_b32 s36, s0, s1
	s_ashr_i32 s37, s36, 31
	s_lshl_b64 s[0:1], s[36:37], 10
	global_load_dword v78, v[10:11], off
	global_load_dword v79, v[10:11], off offset:256
	v_lshl_add_u64 v[10:11], v[8:9], 0, s[0:1]
	s_and_b64 s[0:1], s[40:41], exec
	v_readlane_b32 s0, v252, 54
	v_readlane_b32 s1, v252, 55
	s_cselect_b32 s96, s0, s1
	s_ashr_i32 s97, s96, 31
	s_lshl_b64 s[0:1], s[96:97], 10
	global_load_dword v139, v[10:11], off
	global_load_dword v137, v[10:11], off offset:256
	v_lshl_add_u64 v[10:11], v[8:9], 0, s[0:1]
	s_and_b64 s[0:1], s[40:41], exec
	v_readlane_b32 s0, v252, 56
	v_readlane_b32 s1, v252, 57
	s_cselect_b32 s92, s0, s1
	s_ashr_i32 s93, s92, 31
	s_lshl_b64 s[0:1], s[92:93], 10
	global_load_dword v74, v[10:11], off
	global_load_dword v75, v[10:11], off offset:256
	v_lshl_add_u64 v[10:11], v[8:9], 0, s[0:1]
	s_and_b64 s[0:1], s[40:41], exec
	v_readlane_b32 s0, v252, 58
	v_readlane_b32 s1, v252, 59
	s_cselect_b32 s86, s0, s1
	s_ashr_i32 s87, s86, 31
	s_lshl_b64 s[0:1], s[86:87], 10
	global_load_dword v135, v[10:11], off
	global_load_dword v133, v[10:11], off offset:256
	v_lshl_add_u64 v[10:11], v[8:9], 0, s[0:1]
	s_and_b64 s[0:1], s[40:41], exec
	v_readlane_b32 s0, v252, 60
	v_readlane_b32 s1, v252, 61
	s_cselect_b32 s78, s0, s1
	s_ashr_i32 s79, s78, 31
	s_lshl_b64 s[0:1], s[78:79], 10
	global_load_dword v70, v[10:11], off
	global_load_dword v71, v[10:11], off offset:256
	v_lshl_add_u64 v[10:11], v[8:9], 0, s[0:1]
	s_and_b64 s[0:1], s[40:41], exec
	v_readlane_b32 s0, v252, 62
	v_readlane_b32 s1, v252, 63
	s_cselect_b32 s50, s0, s1
	s_ashr_i32 s51, s50, 31
	s_lshl_b64 s[0:1], s[50:51], 10
	global_load_dword v131, v[10:11], off
	global_load_dword v129, v[10:11], off offset:256
	v_lshl_add_u64 v[10:11], v[8:9], 0, s[0:1]
	s_and_b64 s[0:1], s[40:41], exec
	v_readlane_b32 s0, v253, 0
	v_readlane_b32 s1, v253, 1
	s_cselect_b32 s84, s0, s1
	s_ashr_i32 s85, s84, 31
	s_lshl_b64 s[0:1], s[84:85], 10
	global_load_dword v66, v[10:11], off
	global_load_dword v67, v[10:11], off offset:256
; __global__ void __launch_bounds__(NWAVES * 64, 2) mega_fwd(Args args) {
;     ...
; #pragma unroll
;             for (int q = 0; q < 64; ++q) { const int sidx = seg * 64 + q, c = dir ? 511 - sidx : sidx; er[q] = Eb[(size_t)c * 256]; ei[q] = Eb[(size_t)c * 256 + 64]; }
	v_lshl_add_u64 v[10:11], v[8:9], 0, s[0:1]
	s_and_b64 s[0:1], s[40:41], exec
	v_readlane_b32 s0, v253, 2
	v_readlane_b32 s1, v253, 3
	s_cselect_b32 s26, s0, s1
	s_ashr_i32 s27, s26, 31
	s_lshl_b64 s[0:1], s[26:27], 10
	global_load_dword v127, v[10:11], off
	global_load_dword v125, v[10:11], off offset:256
	v_lshl_add_u64 v[10:11], v[8:9], 0, s[0:1]
	s_and_b64 s[0:1], s[40:41], exec
	v_readlane_b32 s0, v253, 4
	v_readlane_b32 s1, v253, 5
	s_cselect_b32 s22, s0, s1
	s_ashr_i32 s23, s22, 31
	s_lshl_b64 s[0:1], s[22:23], 10
	global_load_dword v62, v[10:11], off
	global_load_dword v63, v[10:11], off offset:256
	v_lshl_add_u64 v[10:11], v[8:9], 0, s[0:1]
	s_and_b64 s[0:1], s[40:41], exec
	v_readlane_b32 s0, v253, 6
	v_readlane_b32 s1, v253, 7
	s_cselect_b32 s8, s0, s1
	s_ashr_i32 s9, s8, 31
	s_lshl_b64 s[0:1], s[8:9], 10
	global_load_dword v123, v[10:11], off
	global_load_dword v121, v[10:11], off offset:256
	v_lshl_add_u64 v[10:11], v[8:9], 0, s[0:1]
	s_and_b64 s[0:1], s[40:41], exec
	v_readlane_b32 s0, v253, 8
	v_readlane_b32 s1, v253, 9
	s_cselect_b32 s6, s0, s1
	s_ashr_i32 s7, s6, 31
	s_lshl_b64 s[0:1], s[6:7], 10
	global_load_dword v84, v[10:11], off
	global_load_dword v85, v[10:11], off offset:256
	v_lshl_add_u64 v[10:11], v[8:9], 0, s[0:1]
	s_and_b64 s[0:1], s[40:41], exec
	v_readlane_b32 s0, v253, 10
	v_readlane_b32 s1, v253, 11
	s_cselect_b32 s80, s0, s1
	s_ashr_i32 s81, s80, 31
	s_lshl_b64 s[0:1], s[80:81], 10
	global_load_dword v146, v[10:11], off
	global_load_dword v144, v[10:11], off offset:256
	v_lshl_add_u64 v[10:11], v[8:9], 0, s[0:1]
	s_and_b64 s[0:1], s[40:41], exec
	v_readlane_b32 s0, v253, 12
	v_readlane_b32 s1, v253, 13
	s_cselect_b32 s94, s0, s1
	s_ashr_i32 s95, s94, 31
	s_lshl_b64 s[0:1], s[94:95], 10
	global_load_dword v80, v[10:11], off
	global_load_dword v81, v[10:11], off offset:256
	v_lshl_add_u64 v[10:11], v[8:9], 0, s[0:1]
	s_and_b64 s[0:1], s[40:41], exec
	v_readlane_b32 s0, v253, 14
	v_readlane_b32 s1, v253, 15
	s_cselect_b32 s90, s0, s1
	s_ashr_i32 s91, s90, 31
	s_lshl_b64 s[0:1], s[90:91], 10
	global_load_dword v142, v[10:11], off
	global_load_dword v140, v[10:11], off offset:256
	v_lshl_add_u64 v[10:11], v[8:9], 0, s[0:1]
	s_and_b64 s[0:1], s[40:41], exec
	v_readlane_b32 s0, v253, 16
	v_readlane_b32 s1, v253, 17
	s_cselect_b32 s82, s0, s1
	s_ashr_i32 s83, s82, 31
	s_lshl_b64 s[0:1], s[82:83], 10
	global_load_dword v76, v[10:11], off
	global_load_dword v77, v[10:11], off offset:256
	v_lshl_add_u64 v[10:11], v[8:9], 0, s[0:1]
	s_and_b64 s[0:1], s[40:41], exec
	v_readlane_b32 s0, v253, 18
	v_readlane_b32 s1, v253, 19
	s_cselect_b32 s74, s0, s1
	s_ashr_i32 s75, s74, 31
	s_lshl_b64 s[0:1], s[74:75], 10
	global_load_dword v138, v[10:11], off
	global_load_dword v136, v[10:11], off offset:256
	v_lshl_add_u64 v[10:11], v[8:9], 0, s[0:1]
	s_and_b64 s[0:1], s[40:41], exec
	v_readlane_b32 s0, v253, 20
	v_readlane_b32 s1, v253, 21
	s_cselect_b32 s48, s0, s1
	s_ashr_i32 s49, s48, 31
	s_lshl_b64 s[0:1], s[48:49], 10
	global_load_dword v72, v[10:11], off
	global_load_dword v73, v[10:11], off offset:256
	v_lshl_add_u64 v[10:11], v[8:9], 0, s[0:1]
	s_and_b64 s[0:1], s[40:41], exec
	v_readlane_b32 s0, v253, 22
	v_readlane_b32 s1, v253, 23
	s_cselect_b32 s72, s0, s1
	s_ashr_i32 s73, s72, 31
	s_lshl_b64 s[0:1], s[72:73], 10
	global_load_dword v134, v[10:11], off
	global_load_dword v132, v[10:11], off offset:256
	v_lshl_add_u64 v[10:11], v[8:9], 0, s[0:1]
	s_and_b64 s[0:1], s[40:41], exec
	v_readlane_b32 s0, v253, 24
	v_readlane_b32 s1, v253, 25
	s_cselect_b32 s24, s0, s1
	s_ashr_i32 s25, s24, 31
	s_lshl_b64 s[0:1], s[24:25], 10
	global_load_dword v68, v[10:11], off
	global_load_dword v69, v[10:11], off offset:256
	v_lshl_add_u64 v[10:11], v[8:9], 0, s[0:1]
	s_and_b64 s[0:1], s[40:41], exec
	v_readlane_b32 s0, v253, 26
	v_readlane_b32 s1, v253, 27
	s_cselect_b32 s20, s0, s1
	s_ashr_i32 s21, s20, 31
	s_lshl_b64 s[0:1], s[20:21], 10
	global_load_dword v130, v[10:11], off
	global_load_dword v128, v[10:11], off offset:256
	v_lshl_add_u64 v[10:11], v[8:9], 0, s[0:1]
	s_and_b64 s[0:1], s[40:41], exec
	v_readlane_b32 s0, v253, 28
	v_readlane_b32 s1, v253, 29
	s_cselect_b32 s18, s0, s1
	s_ashr_i32 s19, s18, 31
	s_lshl_b64 s[0:1], s[18:19], 10
	global_load_dword v64, v[10:11], off
	global_load_dword v65, v[10:11], off offset:256
	v_lshl_add_u64 v[10:11], v[8:9], 0, s[0:1]
	s_and_b64 s[0:1], s[40:41], exec
	v_readlane_b32 s0, v253, 30
	v_readlane_b32 s1, v253, 31
	s_cselect_b32 s16, s0, s1
	s_ashr_i32 s17, s16, 31
	s_lshl_b64 s[0:1], s[16:17], 10
	global_load_dword v126, v[10:11], off
	global_load_dword v124, v[10:11], off offset:256
	v_lshl_add_u64 v[10:11], v[8:9], 0, s[0:1]
	s_and_b64 s[0:1], s[40:41], exec
	v_readlane_b32 s0, v253, 32
	v_readlane_b32 s1, v253, 33
	s_cselect_b32 s14, s0, s1
	s_ashr_i32 s15, s14, 31
	s_lshl_b64 s[0:1], s[14:15], 10
	global_load_dword v60, v[10:11], off
	global_load_dword v61, v[10:11], off offset:256
	v_lshl_add_u64 v[10:11], v[8:9], 0, s[0:1]
	s_and_b64 s[0:1], s[40:41], exec
	v_readlane_b32 s0, v253, 34
	v_readlane_b32 s1, v253, 35
	s_cselect_b32 s12, s0, s1
	s_ashr_i32 s13, s12, 31
	s_lshl_b64 s[0:1], s[12:13], 10
	global_load_dword v122, v[10:11], off
	global_load_dword v120, v[10:11], off offset:256
	v_lshl_add_u64 v[10:11], v[8:9], 0, s[0:1]
	s_and_b64 s[0:1], s[40:41], exec
	v_readlane_b32 s0, v253, 36
	v_readlane_b32 s1, v253, 37
	s_cselect_b32 s60, s0, s1
	s_ashr_i32 s61, s60, 31
	s_lshl_b64 s[0:1], s[60:61], 10
	global_load_dword v58, v[10:11], off
	global_load_dword v59, v[10:11], off offset:256
	v_lshl_add_u64 v[10:11], v[8:9], 0, s[0:1]
	s_and_b64 s[0:1], s[40:41], exec
	v_readlane_b32 s0, v253, 38
; __global__ void __launch_bounds__(NWAVES * 64, 2) mega_fwd(Args args) {
;     ...
; #pragma unroll
;             for (int q = 0; q < 64; ++q) { const int sidx = seg * 64 + q, c = dir ? 511 - sidx : sidx; er[q] = Eb[(size_t)c * 256]; ei[q] = Eb[(size_t)c * 256 + 64]; }
	v_readlane_b32 s1, v253, 39
	s_cselect_b32 s58, s0, s1
	s_ashr_i32 s59, s58, 31
	s_lshl_b64 s[0:1], s[58:59], 10
	global_load_dword v119, v[10:11], off
	global_load_dword v118, v[10:11], off offset:256
	v_lshl_add_u64 v[10:11], v[8:9], 0, s[0:1]
	s_and_b64 s[0:1], s[40:41], exec
	v_readlane_b32 s0, v253, 40
	v_readlane_b32 s1, v253, 41
	s_cselect_b32 s56, s0, s1
	s_ashr_i32 s57, s56, 31
	s_lshl_b64 s[0:1], s[56:57], 10
	global_load_dword v56, v[10:11], off
	global_load_dword v57, v[10:11], off offset:256
	v_lshl_add_u64 v[10:11], v[8:9], 0, s[0:1]
	s_and_b64 s[0:1], s[40:41], exec
	v_readlane_b32 s0, v253, 42
	v_readlane_b32 s1, v253, 43
	s_cselect_b32 s54, s0, s1
	s_ashr_i32 s55, s54, 31
	s_lshl_b64 s[0:1], s[54:55], 10
	global_load_dword v117, v[10:11], off
	global_load_dword v116, v[10:11], off offset:256
	v_lshl_add_u64 v[10:11], v[8:9], 0, s[0:1]
	s_and_b64 s[0:1], s[40:41], exec
	v_readlane_b32 s0, v253, 44
	v_readlane_b32 s1, v253, 45
	s_cselect_b32 s52, s0, s1
	s_ashr_i32 s53, s52, 31
	s_lshl_b64 s[0:1], s[52:53], 10
	global_load_dword v54, v[10:11], off
	global_load_dword v55, v[10:11], off offset:256
	v_lshl_add_u64 v[10:11], v[8:9], 0, s[0:1]
	s_and_b64 s[0:1], s[40:41], exec
	v_readlane_b32 s0, v253, 46
	v_readlane_b32 s1, v253, 47
	s_cselect_b32 s76, s0, s1
	s_ashr_i32 s77, s76, 31
	s_lshl_b64 s[0:1], s[76:77], 10
	global_load_dword v115, v[10:11], off
	global_load_dword v114, v[10:11], off offset:256
	v_lshl_add_u64 v[10:11], v[8:9], 0, s[0:1]
	s_and_b64 s[0:1], s[40:41], exec
	v_readlane_b32 s0, v253, 48
	v_readlane_b32 s1, v253, 49
	s_cselect_b32 s44, s0, s1
	s_ashr_i32 s45, s44, 31
	s_lshl_b64 s[0:1], s[44:45], 10
	global_load_dword v52, v[10:11], off
	global_load_dword v53, v[10:11], off offset:256
	v_lshl_add_u64 v[10:11], v[8:9], 0, s[0:1]
	s_and_b64 s[0:1], s[40:41], exec
	v_readlane_b32 s0, v253, 50
	v_readlane_b32 s1, v253, 51
	s_cselect_b32 s2, s0, s1
	s_ashr_i32 s3, s2, 31
	s_lshl_b64 s[0:1], s[2:3], 10
	global_load_dword v113, v[10:11], off
	global_load_dword v112, v[10:11], off offset:256
	v_lshl_add_u64 v[10:11], v[8:9], 0, s[0:1]
	s_and_b64 s[0:1], s[40:41], exec
	v_readlane_b32 s0, v253, 52
	v_readlane_b32 s1, v253, 53
	s_cselect_b32 s68, s0, s1
	s_ashr_i32 s69, s68, 31
	s_lshl_b64 s[0:1], s[68:69], 10
	global_load_dword v50, v[10:11], off
	global_load_dword v51, v[10:11], off offset:256
	v_lshl_add_u64 v[10:11], v[8:9], 0, s[0:1]
	s_and_b64 s[0:1], s[40:41], exec
	v_readlane_b32 s0, v253, 54
	v_readlane_b32 s1, v253, 55
	s_cselect_b32 s0, s0, s1
	s_ashr_i32 s1, s0, 31
	s_lshl_b64 s[28:29], s[0:1], 10
	global_load_dword v111, v[10:11], off
	global_load_dword v110, v[10:11], off offset:256
	v_lshl_add_u64 v[10:11], v[8:9], 0, s[28:29]
	s_and_b64 s[28:29], s[40:41], exec
	v_readlane_b32 s1, v253, 56
	v_readlane_b32 s3, v253, 57
	s_cselect_b32 s46, s1, s3
	s_ashr_i32 s47, s46, 31
	s_lshl_b64 s[28:29], s[46:47], 10
	global_load_dword v48, v[10:11], off
	global_load_dword v49, v[10:11], off offset:256
	v_lshl_add_u64 v[10:11], v[8:9], 0, s[28:29]
	s_and_b64 s[28:29], s[40:41], exec
	v_readlane_b32 s1, v253, 58
	v_readlane_b32 s3, v253, 59
	s_cselect_b32 s42, s1, s3
	s_ashr_i32 s43, s42, 31
	s_lshl_b64 s[28:29], s[42:43], 10
	global_load_dword v109, v[10:11], off
	global_load_dword v108, v[10:11], off offset:256
	v_lshl_add_u64 v[10:11], v[8:9], 0, s[28:29]
	s_and_b64 s[28:29], s[40:41], exec
	v_readlane_b32 s1, v253, 60
	v_readlane_b32 s3, v253, 61
	s_cselect_b32 s34, s1, s3
	s_ashr_i32 s35, s34, 31
	s_lshl_b64 s[28:29], s[34:35], 10
	global_load_dword v46, v[10:11], off
	global_load_dword v47, v[10:11], off offset:256
	v_lshl_add_u64 v[10:11], v[8:9], 0, s[28:29]
	s_and_b64 s[28:29], s[40:41], exec
	v_readlane_b32 s1, v253, 62
	v_readlane_b32 s3, v253, 63
	s_cselect_b32 s70, s1, s3
	s_ashr_i32 s71, s70, 31
	s_lshl_b64 s[28:29], s[70:71], 10
	global_load_dword v107, v[10:11], off
	global_load_dword v106, v[10:11], off offset:256
	v_lshl_add_u64 v[10:11], v[8:9], 0, s[28:29]
	s_and_b64 s[28:29], s[40:41], exec
	v_readlane_b32 s1, v254, 0
	v_readlane_b32 s3, v254, 1
	s_cselect_b32 s30, s1, s3
	s_ashr_i32 s31, s30, 31
	s_lshl_b64 s[28:29], s[30:31], 10
	global_load_dword v44, v[10:11], off
	global_load_dword v45, v[10:11], off offset:256
	v_lshl_add_u64 v[10:11], v[8:9], 0, s[28:29]
	s_and_b64 s[28:29], s[40:41], exec
	v_readlane_b32 s1, v254, 2
	v_readlane_b32 s3, v254, 3
	s_cselect_b32 s28, s1, s3
	s_ashr_i32 s29, s28, 31
	s_lshl_b64 s[88:89], s[28:29], 10
	global_load_dword v105, v[10:11], off
	global_load_dword v104, v[10:11], off offset:256
	v_lshl_add_u64 v[10:11], v[8:9], 0, s[88:89]
	s_and_b64 s[88:89], s[40:41], exec
	v_readlane_b32 s1, v254, 4
	v_readlane_b32 s3, v254, 5
	s_cselect_b32 vcc_lo, s1, s3
	s_mov_b32 s88, vcc_lo
	s_ashr_i32 vcc_hi, vcc_lo, 31
	v_writelane_b32 v254, s88, 50
	s_lshl_b64 vcc, vcc, 10
	global_load_dword v42, v[10:11], off
	global_load_dword v43, v[10:11], off offset:256
	v_writelane_b32 v254, s89, 51
	v_lshl_add_u64 v[10:11], v[8:9], 0, vcc
	s_and_b64 vcc, s[40:41], exec
	v_readlane_b32 s1, v254, 6
	v_readlane_b32 s3, v254, 7
	s_cselect_b32 vcc_lo, s1, s3
	s_mov_b32 s88, vcc_lo
	s_ashr_i32 vcc_hi, vcc_lo, 31
	v_writelane_b32 v254, s88, 52
	s_lshl_b64 vcc, vcc, 10
	global_load_dword v103, v[10:11], off
	global_load_dword v102, v[10:11], off offset:256
	v_writelane_b32 v254, s89, 53
	v_lshl_add_u64 v[10:11], v[8:9], 0, vcc
	s_and_b64 vcc, s[40:41], exec
	v_readlane_b32 s1, v254, 8
	v_readlane_b32 s3, v254, 9
	s_cselect_b32 vcc_lo, s1, s3
	s_mov_b32 s88, vcc_lo
	s_ashr_i32 vcc_hi, vcc_lo, 31
	v_writelane_b32 v254, s88, 54
	s_lshl_b64 vcc, vcc, 10
	global_load_dword v40, v[10:11], off
; __device__ __forceinline__ void sincos_rev(float rev, float& s, float& c) { const float f = rev - floorf(rev); s = __builtin_amdgcn_sinf(f); c = __builtin_amdgcn_cosf(f); }
; __global__ void __launch_bounds__(NWAVES * 64, 2) mega_fwd(Args args) {
;     ...
;             const float mag = expf(16.0f * delta * lr); float sn, cs; { const double rev = 16.0 * (double)delta * (double)li * 0.15915494309189535; sincos_rev((float)(rev - floor(rev)), sn, cs); }
;             const float ar = mag * cs, ai = mag * sn;
;             const float* Eb = EB + ((size_t)(g * 1024 + b * 512)) * 256 + dir * 128 + p;
;             bf16* Ab = AUG + ((size_t)(g * 1024 + b * 512)) * 512 + 256 + dir * 128 + p;
;             float er[64], ei[64];
; #pragma unroll
;             for (int q = 0; q < 64; ++q) { const int sidx = seg * 64 + q, c = dir ? 511 - sidx : sidx; er[q] = Eb[(size_t)c * 256]; ei[q] = Eb[(size_t)c * 256 + 64]; }
;             float sr = 0.f, si = 0.f;
; #pragma unroll
;             for (int q = 0; q < 64; ++q) { const float nr = ar * sr - ai * si + er[q], ni = ar * si + ai * sr + ei[q]; sr = nr; si = ni; }
	global_load_dword v41, v[10:11], off offset:256
	v_writelane_b32 v254, s89, 55
	v_lshl_add_u64 v[10:11], v[8:9], 0, vcc
	s_and_b64 vcc, s[40:41], exec
	v_readlane_b32 s1, v254, 10
	v_readlane_b32 s3, v254, 11
	s_cselect_b32 vcc_lo, s1, s3
	s_mov_b32 s88, vcc_lo
	s_ashr_i32 vcc_hi, vcc_lo, 31
	v_writelane_b32 v254, s88, 56
	s_lshl_b64 vcc, vcc, 10
	global_load_dword v101, v[10:11], off
	global_load_dword v100, v[10:11], off offset:256
	v_writelane_b32 v254, s89, 57
	v_lshl_add_u64 v[10:11], v[8:9], 0, vcc
	s_and_b64 vcc, s[40:41], exec
	v_readlane_b32 s1, v254, 12
	v_readlane_b32 s3, v254, 13
	s_cselect_b32 vcc_lo, s1, s3
	s_mov_b32 s88, vcc_lo
	s_ashr_i32 vcc_hi, vcc_lo, 31
	v_writelane_b32 v254, s88, 58
	s_lshl_b64 vcc, vcc, 10
	global_load_dword v38, v[10:11], off
	global_load_dword v39, v[10:11], off offset:256
	v_writelane_b32 v254, s89, 59
	v_lshl_add_u64 v[10:11], v[8:9], 0, vcc
	s_and_b64 vcc, s[40:41], exec
	v_readlane_b32 s1, v254, 14
	v_readlane_b32 s3, v254, 15
	s_cselect_b32 vcc_lo, s1, s3
	s_mov_b32 s88, vcc_lo
	s_ashr_i32 vcc_hi, vcc_lo, 31
	v_writelane_b32 v254, s88, 60
	s_lshl_b64 vcc, vcc, 10
	global_load_dword v99, v[10:11], off
	global_load_dword v98, v[10:11], off offset:256
	v_writelane_b32 v254, s89, 61
	v_lshl_add_u64 v[10:11], v[8:9], 0, vcc
	s_and_b64 vcc, s[40:41], exec
	v_readlane_b32 s1, v254, 16
	v_readlane_b32 s3, v254, 17
	s_cselect_b32 vcc_lo, s1, s3
	s_mov_b32 s88, vcc_lo
	s_ashr_i32 vcc_hi, vcc_lo, 31
	v_writelane_b32 v254, s88, 62
	s_lshl_b64 vcc, vcc, 10
	global_load_dword v37, v[10:11], off
	global_load_dword v36, v[10:11], off offset:256
	v_writelane_b32 v254, s89, 63
	v_lshl_add_u64 v[10:11], v[8:9], 0, vcc
	s_and_b64 vcc, s[40:41], exec
	v_readlane_b32 s1, v254, 18
	v_readlane_b32 s3, v254, 19
	s_cselect_b32 vcc_lo, s1, s3
	s_ashr_i32 vcc_hi, vcc_lo, 31
	s_mov_b32 s88, vcc_lo
	s_lshl_b64 vcc, vcc, 10
	global_load_dword v35, v[10:11], off
	global_load_dword v34, v[10:11], off offset:256
	v_lshl_add_u64 v[10:11], v[8:9], 0, vcc
	s_and_b64 vcc, s[40:41], exec
	v_readlane_b32 s1, v254, 20
	v_readlane_b32 s3, v254, 21
	s_cselect_b32 vcc_lo, s1, s3
	v_writelane_b32 v250, s88, 0
	s_ashr_i32 vcc_hi, vcc_lo, 31
	global_load_dword v33, v[10:11], off
	global_load_dword v32, v[10:11], off offset:256
	v_writelane_b32 v250, s89, 1
	s_mov_b32 s88, vcc_lo
	s_lshl_b64 vcc, vcc, 10
	v_lshl_add_u64 v[10:11], v[8:9], 0, vcc
	s_and_b64 vcc, s[40:41], exec
	v_readlane_b32 s1, v254, 22
	v_readlane_b32 s3, v254, 23
	s_cselect_b32 vcc_lo, s1, s3
	v_writelane_b32 v250, s88, 2
	s_ashr_i32 vcc_hi, vcc_lo, 31
	global_load_dword v31, v[10:11], off
	global_load_dword v30, v[10:11], off offset:256
	v_writelane_b32 v250, s89, 3
	s_mov_b32 s88, vcc_lo
	s_lshl_b64 vcc, vcc, 10
	v_lshl_add_u64 v[10:11], v[8:9], 0, vcc
	s_and_b64 vcc, s[40:41], exec
	v_readlane_b32 s1, v254, 24
	v_readlane_b32 s3, v254, 25
	s_cselect_b32 vcc_lo, s1, s3
	v_writelane_b32 v250, s88, 4
	s_ashr_i32 vcc_hi, vcc_lo, 31
	global_load_dword v28, v[10:11], off
	global_load_dword v29, v[10:11], off offset:256
	v_writelane_b32 v250, s89, 5
	s_mov_b32 s88, vcc_lo
	s_lshl_b64 vcc, vcc, 10
	v_lshl_add_u64 v[10:11], v[8:9], 0, vcc
	s_and_b64 vcc, s[40:41], exec
	v_readlane_b32 s1, v254, 26
	v_readlane_b32 s3, v254, 27
	s_cselect_b32 vcc_lo, s1, s3
	v_writelane_b32 v250, s88, 6
	s_ashr_i32 vcc_hi, vcc_lo, 31
	global_load_dword v26, v[10:11], off
	global_load_dword v27, v[10:11], off offset:256
	v_writelane_b32 v250, s89, 7
	s_mov_b32 s88, vcc_lo
	s_lshl_b64 vcc, vcc, 10
	v_lshl_add_u64 v[10:11], v[8:9], 0, vcc
	s_and_b64 vcc, s[40:41], exec
	v_readlane_b32 s1, v254, 28
	v_readlane_b32 s3, v254, 29
	s_cselect_b32 vcc_lo, s1, s3
	v_writelane_b32 v250, s88, 8
	s_ashr_i32 vcc_hi, vcc_lo, 31
	global_load_dword v24, v[10:11], off
	global_load_dword v25, v[10:11], off offset:256
	v_writelane_b32 v250, s89, 9
	s_mov_b32 s88, vcc_lo
	s_lshl_b64 vcc, vcc, 10
	v_lshl_add_u64 v[10:11], v[8:9], 0, vcc
	s_and_b64 vcc, s[40:41], exec
	v_readlane_b32 s1, v254, 30
	v_readlane_b32 s3, v254, 31
	s_cselect_b32 vcc_lo, s1, s3
	v_writelane_b32 v250, s88, 10
	s_ashr_i32 vcc_hi, vcc_lo, 31
	global_load_dword v22, v[10:11], off
	global_load_dword v23, v[10:11], off offset:256
	v_writelane_b32 v250, s89, 11
	s_mov_b32 s88, vcc_lo
	s_lshl_b64 vcc, vcc, 10
	v_lshl_add_u64 v[10:11], v[8:9], 0, vcc
	s_and_b64 vcc, s[40:41], exec
	v_readlane_b32 s1, v254, 32
	v_readlane_b32 s3, v254, 33
	s_cselect_b32 vcc_lo, s1, s3
	v_writelane_b32 v250, s88, 12
	s_ashr_i32 vcc_hi, vcc_lo, 31
	global_load_dword v20, v[10:11], off
	global_load_dword v21, v[10:11], off offset:256
	v_writelane_b32 v250, s89, 13
	s_mov_b32 s88, vcc_lo
	s_lshl_b64 vcc, vcc, 10
	v_lshl_add_u64 v[10:11], v[8:9], 0, vcc
	s_and_b64 vcc, s[40:41], exec
	v_readlane_b32 s1, v254, 34
	v_readlane_b32 s3, v254, 35
	s_cselect_b32 vcc_lo, s1, s3
	v_writelane_b32 v250, s88, 14
	s_ashr_i32 vcc_hi, vcc_lo, 31
	global_load_dword v18, v[10:11], off
	global_load_dword v19, v[10:11], off offset:256
	v_writelane_b32 v250, s89, 15
	s_mov_b32 s88, vcc_lo
	s_lshl_b64 vcc, vcc, 10
	v_lshl_add_u64 v[10:11], v[8:9], 0, vcc
	s_and_b64 vcc, s[40:41], exec
	v_readlane_b32 s1, v254, 36
	v_readlane_b32 s3, v254, 37
	s_cselect_b32 vcc_lo, s1, s3
	v_writelane_b32 v250, s88, 16
	s_ashr_i32 vcc_hi, vcc_lo, 31
	global_load_dword v16, v[10:11], off
	global_load_dword v17, v[10:11], off offset:256
	v_writelane_b32 v250, s89, 17
	s_mov_b32 s88, vcc_lo
	s_lshl_b64 vcc, vcc, 10
	v_lshl_add_u64 v[10:11], v[8:9], 0, vcc
	s_and_b64 vcc, s[40:41], exec
	v_readlane_b32 s1, v254, 38
	v_readlane_b32 s3, v254, 39
	s_cselect_b32 vcc_lo, s1, s3
	v_writelane_b32 v250, s88, 18
	s_ashr_i32 vcc_hi, vcc_lo, 31
	global_load_dword v14, v[10:11], off
	global_load_dword v15, v[10:11], off offset:256
	v_writelane_b32 v250, s89, 19
	s_mov_b32 s88, vcc_lo
	s_lshl_b64 vcc, vcc, 10
	v_lshl_add_u64 v[10:11], v[8:9], 0, vcc
	s_and_b64 vcc, s[40:41], exec
	v_readlane_b32 s1, v254, 41
	v_readlane_b32 s3, v254, 42
	s_cselect_b32 vcc_lo, s1, s3
	v_writelane_b32 v250, s88, 20
	s_ashr_i32 vcc_hi, vcc_lo, 31
	v_cos_f32_e32 v88, v3
	v_writelane_b32 v250, s89, 21
	s_mov_b32 s88, vcc_lo
	s_lshl_b64 vcc, vcc, 10
	v_sin_f32_e32 v89, v3
	v_writelane_b32 v252, s88, 0
	v_lshl_add_u64 v[90:91], v[8:9], 0, vcc
	s_and_b64 vcc, s[40:41], exec
	v_readlane_b32 s1, v254, 43
	v_readlane_b32 s3, v254, 44
	v_writelane_b32 v252, s89, 1
	s_cselect_b32 s88, s1, s3
	s_mov_b32 vcc_lo, s88
	s_ashr_i32 s89, s88, 31
	v_writelane_b32 v252, vcc_lo, 2
	v_pk_mul_f32 v[86:87], v[86:87], v[88:89] op_sel_hi:[0,1]
	v_mul_f32_e32 v88, 0, v86
	v_mul_f32_e32 v89, 0, v87
	v_writelane_b32 v252, vcc_hi, 3
	s_lshl_b64 vcc, s[88:89], 10
	global_load_dword v12, v[10:11], off
	global_load_dword v13, v[10:11], off offset:256
	s_nop 0
	global_load_dword v10, v[90:91], off
	global_load_dword v11, v[90:91], off offset:256
	v_lshl_add_u64 v[90:91], v[8:9], 0, vcc
	v_sub_f32_e32 v3, v88, v89
	global_load_dword v8, v[90:91], off
	global_load_dword v9, v[90:91], off offset:256
	s_waitcnt vmcnt(62)
; __global__ void __launch_bounds__(NWAVES * 64, 2) mega_fwd(Args args) {
;     ...
;             for (int q = 0; q < 64; ++q) { const float nr = ar * sr - ai * si + er[q], ni = ar * si + ai * sr + ei[q]; sr = nr; si = ni; }
	v_add_f32_e32 v90, v3, v147
	v_add_f32_e32 v3, v88, v89
	v_add_f32_e32 v88, v3, v145
	v_pk_mul_f32 v[88:89], v[86:87], v[88:89] op_sel:[1,0] op_sel_hi:[0,0]
	v_pk_fma_f32 v[92:93], v[86:87], v[90:91], v[88:89] neg_lo:[0,0,1] neg_hi:[0,0,1]
	v_pk_fma_f32 v[88:89], v[86:87], v[90:91], v[88:89] op_sel_hi:[1,0,1]
	v_readlane_b32 vcc_lo, v252, 41
	v_mov_b32_e32 v93, v89
	v_add_f32_e32 v88, v92, v82
	v_add_f32_e32 v89, v93, v83
	v_readlane_b32 vcc_hi, v252, 42
	v_mul_f32_e32 v90, v86, v88
	v_mul_f32_e32 v91, v87, v89
	v_pk_mul_f32 v[88:89], v[86:87], v[88:89] op_sel:[0,1] op_sel_hi:[1,0]
	v_sub_f32_e32 v3, v90, v91
	v_add_f32_e32 v90, v3, v143
	v_add_f32_e32 v3, v88, v89
	v_add_f32_e32 v88, v3, v141
	v_pk_mul_f32 v[88:89], v[86:87], v[88:89] op_sel:[1,0] op_sel_hi:[0,0]
	v_pk_fma_f32 v[92:93], v[86:87], v[90:91], v[88:89] neg_lo:[0,0,1] neg_hi:[0,0,1]
	v_pk_fma_f32 v[88:89], v[86:87], v[90:91], v[88:89] op_sel_hi:[1,0,1]
	s_andn2_b64 vcc, exec, vcc
	v_mov_b32_e32 v93, v89
	v_add_f32_e32 v88, v92, v78
	v_add_f32_e32 v89, v93, v79
	s_nop 0
	v_mul_f32_e32 v90, v86, v88
	v_mul_f32_e32 v91, v87, v89
	v_pk_mul_f32 v[88:89], v[86:87], v[88:89] op_sel:[0,1] op_sel_hi:[1,0]
	v_sub_f32_e32 v3, v90, v91
	v_add_f32_e32 v90, v3, v139
	v_add_f32_e32 v3, v88, v89
	v_add_f32_e32 v88, v3, v137
	v_pk_mul_f32 v[88:89], v[86:87], v[88:89] op_sel:[1,0] op_sel_hi:[0,0]
	v_pk_fma_f32 v[92:93], v[86:87], v[90:91], v[88:89] neg_lo:[0,0,1] neg_hi:[0,0,1]
	v_pk_fma_f32 v[88:89], v[86:87], v[90:91], v[88:89] op_sel_hi:[1,0,1]
	s_nop 0
	v_mov_b32_e32 v93, v89
	v_add_f32_e32 v88, v92, v74
	v_add_f32_e32 v89, v93, v75
	s_nop 0
	v_mul_f32_e32 v90, v86, v88
	v_mul_f32_e32 v91, v87, v89
	v_pk_mul_f32 v[88:89], v[86:87], v[88:89] op_sel:[0,1] op_sel_hi:[1,0]
	v_sub_f32_e32 v3, v90, v91
	v_add_f32_e32 v90, v3, v135
	v_add_f32_e32 v3, v88, v89
	v_add_f32_e32 v88, v3, v133
	v_pk_mul_f32 v[88:89], v[86:87], v[88:89] op_sel:[1,0] op_sel_hi:[0,0]
	v_pk_fma_f32 v[92:93], v[86:87], v[90:91], v[88:89] neg_lo:[0,0,1] neg_hi:[0,0,1]
	v_pk_fma_f32 v[88:89], v[86:87], v[90:91], v[88:89] op_sel_hi:[1,0,1]
	s_nop 0
	v_mov_b32_e32 v93, v89
	v_add_f32_e32 v88, v92, v70
	v_add_f32_e32 v89, v93, v71
	s_nop 0
	v_mul_f32_e32 v90, v86, v88
	v_mul_f32_e32 v91, v87, v89
	v_pk_mul_f32 v[88:89], v[86:87], v[88:89] op_sel:[0,1] op_sel_hi:[1,0]
	v_sub_f32_e32 v3, v90, v91
	v_add_f32_e32 v90, v3, v131
	v_add_f32_e32 v3, v88, v89
	v_add_f32_e32 v88, v3, v129
	v_pk_mul_f32 v[88:89], v[86:87], v[88:89] op_sel:[1,0] op_sel_hi:[0,0]
	v_pk_fma_f32 v[92:93], v[86:87], v[90:91], v[88:89] neg_lo:[0,0,1] neg_hi:[0,0,1]
	v_pk_fma_f32 v[88:89], v[86:87], v[90:91], v[88:89] op_sel_hi:[1,0,1]
	s_nop 0
	v_mov_b32_e32 v93, v89
	v_add_f32_e32 v88, v92, v66
	v_add_f32_e32 v89, v93, v67
	s_nop 0
	v_mul_f32_e32 v90, v86, v88
	v_mul_f32_e32 v91, v87, v89
	v_pk_mul_f32 v[88:89], v[86:87], v[88:89] op_sel:[0,1] op_sel_hi:[1,0]
	v_sub_f32_e32 v3, v90, v91
	v_add_f32_e32 v90, v3, v127
	v_add_f32_e32 v3, v88, v89
	v_add_f32_e32 v88, v3, v125
	v_pk_mul_f32 v[88:89], v[86:87], v[88:89] op_sel:[1,0] op_sel_hi:[0,0]
	v_pk_fma_f32 v[92:93], v[86:87], v[90:91], v[88:89] neg_lo:[0,0,1] neg_hi:[0,0,1]
	v_pk_fma_f32 v[88:89], v[86:87], v[90:91], v[88:89] op_sel_hi:[1,0,1]
	s_nop 0
	v_mov_b32_e32 v93, v89
	v_add_f32_e32 v88, v92, v62
	v_add_f32_e32 v89, v93, v63
	s_nop 0
	v_mul_f32_e32 v90, v86, v88
	v_mul_f32_e32 v91, v87, v89
	v_pk_mul_f32 v[88:89], v[86:87], v[88:89] op_sel:[0,1] op_sel_hi:[1,0]
	v_sub_f32_e32 v3, v90, v91
	v_add_f32_e32 v90, v3, v123
	v_add_f32_e32 v3, v88, v89
	v_add_f32_e32 v88, v3, v121
	v_pk_mul_f32 v[88:89], v[86:87], v[88:89] op_sel:[1,0] op_sel_hi:[0,0]
	v_pk_fma_f32 v[92:93], v[86:87], v[90:91], v[88:89] neg_lo:[0,0,1] neg_hi:[0,0,1]
	v_pk_fma_f32 v[88:89], v[86:87], v[90:91], v[88:89] op_sel_hi:[1,0,1]
	s_nop 0
	v_mov_b32_e32 v93, v89
	v_add_f32_e32 v88, v92, v84
	v_add_f32_e32 v89, v93, v85
	s_nop 0
	v_mul_f32_e32 v90, v86, v88
	v_mul_f32_e32 v91, v87, v89
	v_pk_mul_f32 v[88:89], v[86:87], v[88:89] op_sel:[0,1] op_sel_hi:[1,0]
	v_sub_f32_e32 v3, v90, v91
	v_add_f32_e32 v90, v3, v146
	v_add_f32_e32 v3, v88, v89
	v_add_f32_e32 v88, v3, v144
	v_pk_mul_f32 v[88:89], v[86:87], v[88:89] op_sel:[1,0] op_sel_hi:[0,0]
	v_pk_fma_f32 v[92:93], v[86:87], v[90:91], v[88:89] neg_lo:[0,0,1] neg_hi:[0,0,1]
	v_pk_fma_f32 v[88:89], v[86:87], v[90:91], v[88:89] op_sel_hi:[1,0,1]
	s_nop 0
	v_mov_b32_e32 v93, v89
	v_add_f32_e32 v88, v92, v80
	v_add_f32_e32 v89, v93, v81
	s_nop 0
	v_mul_f32_e32 v90, v86, v88
	v_mul_f32_e32 v91, v87, v89
	v_pk_mul_f32 v[88:89], v[86:87], v[88:89] op_sel:[0,1] op_sel_hi:[1,0]
	v_sub_f32_e32 v3, v90, v91
	v_add_f32_e32 v90, v3, v142
	v_add_f32_e32 v3, v88, v89
	v_add_f32_e32 v88, v3, v140
	v_pk_mul_f32 v[88:89], v[86:87], v[88:89] op_sel:[1,0] op_sel_hi:[0,0]
	v_pk_fma_f32 v[92:93], v[86:87], v[90:91], v[88:89] neg_lo:[0,0,1] neg_hi:[0,0,1]
	v_pk_fma_f32 v[88:89], v[86:87], v[90:91], v[88:89] op_sel_hi:[1,0,1]
	s_nop 0
	v_mov_b32_e32 v93, v89
	v_add_f32_e32 v88, v92, v76
	v_add_f32_e32 v89, v93, v77
	s_nop 0
	v_mul_f32_e32 v90, v86, v88
	v_mul_f32_e32 v91, v87, v89
	v_pk_mul_f32 v[88:89], v[86:87], v[88:89] op_sel:[0,1] op_sel_hi:[1,0]
	v_sub_f32_e32 v3, v90, v91
	v_add_f32_e32 v90, v3, v138
	v_add_f32_e32 v3, v88, v89
	v_add_f32_e32 v88, v3, v136
	v_pk_mul_f32 v[88:89], v[86:87], v[88:89] op_sel:[1,0] op_sel_hi:[0,0]
	v_pk_fma_f32 v[92:93], v[86:87], v[90:91], v[88:89] neg_lo:[0,0,1] neg_hi:[0,0,1]
	v_pk_fma_f32 v[88:89], v[86:87], v[90:91], v[88:89] op_sel_hi:[1,0,1]
	s_nop 0
	v_mov_b32_e32 v93, v89
	v_add_f32_e32 v88, v92, v72
	v_add_f32_e32 v89, v93, v73
	s_nop 0
	v_mul_f32_e32 v90, v86, v88
; __global__ void __launch_bounds__(NWAVES * 64, 2) mega_fwd(Args args) {
;     ...
;             for (int q = 0; q < 64; ++q) { const float nr = ar * sr - ai * si + er[q], ni = ar * si + ai * sr + ei[q]; sr = nr; si = ni; }
	v_mul_f32_e32 v91, v87, v89
	v_pk_mul_f32 v[88:89], v[86:87], v[88:89] op_sel:[0,1] op_sel_hi:[1,0]
	v_sub_f32_e32 v3, v90, v91
	v_add_f32_e32 v90, v3, v134
	v_add_f32_e32 v3, v88, v89
	v_add_f32_e32 v88, v3, v132
	v_pk_mul_f32 v[88:89], v[86:87], v[88:89] op_sel:[1,0] op_sel_hi:[0,0]
	v_pk_fma_f32 v[92:93], v[86:87], v[90:91], v[88:89] neg_lo:[0,0,1] neg_hi:[0,0,1]
	v_pk_fma_f32 v[88:89], v[86:87], v[90:91], v[88:89] op_sel_hi:[1,0,1]
	s_nop 0
	v_mov_b32_e32 v93, v89
	v_add_f32_e32 v88, v92, v68
	v_add_f32_e32 v89, v93, v69
	s_nop 0
	v_mul_f32_e32 v90, v86, v88
	v_mul_f32_e32 v91, v87, v89
	v_pk_mul_f32 v[88:89], v[86:87], v[88:89] op_sel:[0,1] op_sel_hi:[1,0]
	v_sub_f32_e32 v3, v90, v91
	v_add_f32_e32 v90, v3, v130
	v_add_f32_e32 v3, v88, v89
	v_add_f32_e32 v88, v3, v128
	v_pk_mul_f32 v[88:89], v[86:87], v[88:89] op_sel:[1,0] op_sel_hi:[0,0]
	v_pk_fma_f32 v[92:93], v[86:87], v[90:91], v[88:89] neg_lo:[0,0,1] neg_hi:[0,0,1]
	v_pk_fma_f32 v[88:89], v[86:87], v[90:91], v[88:89] op_sel_hi:[1,0,1]
	s_nop 0
	v_mov_b32_e32 v93, v89
	v_add_f32_e32 v88, v92, v64
	v_add_f32_e32 v89, v93, v65
	s_nop 0
	v_mul_f32_e32 v90, v86, v88
	v_mul_f32_e32 v91, v87, v89
	v_pk_mul_f32 v[88:89], v[86:87], v[88:89] op_sel:[0,1] op_sel_hi:[1,0]
	v_sub_f32_e32 v3, v90, v91
	v_add_f32_e32 v90, v3, v126
	v_add_f32_e32 v3, v88, v89
	v_add_f32_e32 v88, v3, v124
	v_pk_mul_f32 v[88:89], v[86:87], v[88:89] op_sel:[1,0] op_sel_hi:[0,0]
	v_pk_fma_f32 v[92:93], v[86:87], v[90:91], v[88:89] neg_lo:[0,0,1] neg_hi:[0,0,1]
	v_pk_fma_f32 v[88:89], v[86:87], v[90:91], v[88:89] op_sel_hi:[1,0,1]
	s_nop 0
	v_mov_b32_e32 v93, v89
	v_add_f32_e32 v88, v92, v60
	v_add_f32_e32 v89, v93, v61
	s_nop 0
	v_mul_f32_e32 v90, v86, v88
	v_mul_f32_e32 v91, v87, v89
	v_pk_mul_f32 v[88:89], v[86:87], v[88:89] op_sel:[0,1] op_sel_hi:[1,0]
	v_sub_f32_e32 v3, v90, v91
	v_add_f32_e32 v90, v3, v122
	v_add_f32_e32 v3, v88, v89
	v_add_f32_e32 v88, v3, v120
	v_pk_mul_f32 v[88:89], v[86:87], v[88:89] op_sel:[1,0] op_sel_hi:[0,0]
	v_pk_fma_f32 v[92:93], v[86:87], v[90:91], v[88:89] neg_lo:[0,0,1] neg_hi:[0,0,1]
	v_pk_fma_f32 v[88:89], v[86:87], v[90:91], v[88:89] op_sel_hi:[1,0,1]
	s_nop 0
	v_mov_b32_e32 v93, v89
	v_add_f32_e32 v88, v92, v58
	v_add_f32_e32 v89, v93, v59
	s_nop 0
	v_mul_f32_e32 v90, v86, v88
	v_mul_f32_e32 v91, v87, v89
	v_pk_mul_f32 v[88:89], v[86:87], v[88:89] op_sel:[0,1] op_sel_hi:[1,0]
	v_sub_f32_e32 v3, v90, v91
	v_add_f32_e32 v90, v3, v119
	v_add_f32_e32 v3, v88, v89
	v_add_f32_e32 v88, v3, v118
	v_pk_mul_f32 v[88:89], v[86:87], v[88:89] op_sel:[1,0] op_sel_hi:[0,0]
	v_pk_fma_f32 v[92:93], v[86:87], v[90:91], v[88:89] neg_lo:[0,0,1] neg_hi:[0,0,1]
	v_pk_fma_f32 v[88:89], v[86:87], v[90:91], v[88:89] op_sel_hi:[1,0,1]
	s_nop 0
	v_mov_b32_e32 v93, v89
	v_add_f32_e32 v88, v92, v56
	v_add_f32_e32 v89, v93, v57
	s_nop 0
	v_mul_f32_e32 v90, v86, v88
	v_mul_f32_e32 v91, v87, v89
	v_pk_mul_f32 v[88:89], v[86:87], v[88:89] op_sel:[0,1] op_sel_hi:[1,0]
	v_sub_f32_e32 v3, v90, v91
	v_add_f32_e32 v90, v3, v117
	v_add_f32_e32 v3, v88, v89
	v_add_f32_e32 v88, v3, v116
	v_pk_mul_f32 v[88:89], v[86:87], v[88:89] op_sel:[1,0] op_sel_hi:[0,0]
	v_pk_fma_f32 v[92:93], v[86:87], v[90:91], v[88:89] neg_lo:[0,0,1] neg_hi:[0,0,1]
	v_pk_fma_f32 v[88:89], v[86:87], v[90:91], v[88:89] op_sel_hi:[1,0,1]
	s_nop 0
	v_mov_b32_e32 v93, v89
	v_add_f32_e32 v88, v92, v54
	v_add_f32_e32 v89, v93, v55
	s_nop 0
	v_mul_f32_e32 v90, v86, v88
	v_mul_f32_e32 v91, v87, v89
	v_pk_mul_f32 v[88:89], v[86:87], v[88:89] op_sel:[0,1] op_sel_hi:[1,0]
	v_sub_f32_e32 v3, v90, v91
	v_add_f32_e32 v90, v3, v115
	v_add_f32_e32 v3, v88, v89
	v_add_f32_e32 v88, v3, v114
	v_pk_mul_f32 v[88:89], v[86:87], v[88:89] op_sel:[1,0] op_sel_hi:[0,0]
	v_pk_fma_f32 v[92:93], v[86:87], v[90:91], v[88:89] neg_lo:[0,0,1] neg_hi:[0,0,1]
	v_pk_fma_f32 v[88:89], v[86:87], v[90:91], v[88:89] op_sel_hi:[1,0,1]
	s_nop 0
	v_mov_b32_e32 v93, v89
	s_waitcnt vmcnt(60)
	v_add_f32_e32 v88, v92, v52
	v_add_f32_e32 v89, v93, v53
	s_nop 0
	v_mul_f32_e32 v90, v86, v88
	v_mul_f32_e32 v91, v87, v89
	v_pk_mul_f32 v[88:89], v[86:87], v[88:89] op_sel:[0,1] op_sel_hi:[1,0]
	v_sub_f32_e32 v3, v90, v91
	s_waitcnt vmcnt(59)
	v_add_f32_e32 v90, v3, v113
	v_add_f32_e32 v3, v88, v89
	s_waitcnt vmcnt(58)
	v_add_f32_e32 v88, v3, v112
	v_pk_mul_f32 v[88:89], v[86:87], v[88:89] op_sel:[1,0] op_sel_hi:[0,0]
	v_pk_fma_f32 v[92:93], v[86:87], v[90:91], v[88:89] neg_lo:[0,0,1] neg_hi:[0,0,1]
	v_pk_fma_f32 v[88:89], v[86:87], v[90:91], v[88:89] op_sel_hi:[1,0,1]
	s_nop 0
	v_mov_b32_e32 v93, v89
	s_waitcnt vmcnt(56)
	v_add_f32_e32 v88, v92, v50
	v_add_f32_e32 v89, v93, v51
	s_nop 0
	v_mul_f32_e32 v90, v86, v88
	v_mul_f32_e32 v91, v87, v89
	v_pk_mul_f32 v[88:89], v[86:87], v[88:89] op_sel:[0,1] op_sel_hi:[1,0]
	v_sub_f32_e32 v3, v90, v91
	s_waitcnt vmcnt(55)
	v_add_f32_e32 v90, v3, v111
	v_add_f32_e32 v3, v88, v89
	s_waitcnt vmcnt(54)
	v_add_f32_e32 v88, v3, v110
	v_pk_mul_f32 v[88:89], v[86:87], v[88:89] op_sel:[1,0] op_sel_hi:[0,0]
	v_pk_fma_f32 v[92:93], v[86:87], v[90:91], v[88:89] neg_lo:[0,0,1] neg_hi:[0,0,1]
	v_pk_fma_f32 v[88:89], v[86:87], v[90:91], v[88:89] op_sel_hi:[1,0,1]
	s_nop 0
	v_mov_b32_e32 v93, v89
	s_waitcnt vmcnt(52)
	v_add_f32_e32 v88, v92, v48
	v_add_f32_e32 v89, v93, v49
	s_nop 0
	v_mul_f32_e32 v90, v86, v88
	v_mul_f32_e32 v91, v87, v89
	v_pk_mul_f32 v[88:89], v[86:87], v[88:89] op_sel:[0,1] op_sel_hi:[1,0]
	v_sub_f32_e32 v3, v90, v91
	s_waitcnt vmcnt(51)
	v_add_f32_e32 v90, v3, v109
	v_add_f32_e32 v3, v88, v89
	s_waitcnt vmcnt(50)
; __global__ void __launch_bounds__(NWAVES * 64, 2) mega_fwd(Args args) {
;     ...
;             for (int q = 0; q < 64; ++q) { const float nr = ar * sr - ai * si + er[q], ni = ar * si + ai * sr + ei[q]; sr = nr; si = ni; }
	v_add_f32_e32 v88, v3, v108
	v_pk_mul_f32 v[88:89], v[86:87], v[88:89] op_sel:[1,0] op_sel_hi:[0,0]
	v_pk_fma_f32 v[92:93], v[86:87], v[90:91], v[88:89] neg_lo:[0,0,1] neg_hi:[0,0,1]
	v_pk_fma_f32 v[88:89], v[86:87], v[90:91], v[88:89] op_sel_hi:[1,0,1]
	s_nop 0
	v_mov_b32_e32 v93, v89
	s_waitcnt vmcnt(48)
	v_add_f32_e32 v88, v92, v46
	v_add_f32_e32 v89, v93, v47
	s_nop 0
	v_mul_f32_e32 v90, v86, v88
	v_mul_f32_e32 v91, v87, v89
	v_pk_mul_f32 v[88:89], v[86:87], v[88:89] op_sel:[0,1] op_sel_hi:[1,0]
	v_sub_f32_e32 v3, v90, v91
	s_waitcnt vmcnt(47)
	v_add_f32_e32 v90, v3, v107
	v_add_f32_e32 v3, v88, v89
	s_waitcnt vmcnt(46)
	v_add_f32_e32 v88, v3, v106
	v_pk_mul_f32 v[88:89], v[86:87], v[88:89] op_sel:[1,0] op_sel_hi:[0,0]
	v_pk_fma_f32 v[92:93], v[86:87], v[90:91], v[88:89] neg_lo:[0,0,1] neg_hi:[0,0,1]
	v_pk_fma_f32 v[88:89], v[86:87], v[90:91], v[88:89] op_sel_hi:[1,0,1]
	s_nop 0
	v_mov_b32_e32 v93, v89
	s_waitcnt vmcnt(44)
	v_add_f32_e32 v88, v92, v44
	v_add_f32_e32 v89, v93, v45
	s_nop 0
	v_mul_f32_e32 v90, v86, v88
	v_mul_f32_e32 v91, v87, v89
	v_pk_mul_f32 v[88:89], v[86:87], v[88:89] op_sel:[0,1] op_sel_hi:[1,0]
	v_sub_f32_e32 v3, v90, v91
	s_waitcnt vmcnt(43)
	v_add_f32_e32 v90, v3, v105
	v_add_f32_e32 v3, v88, v89
	s_waitcnt vmcnt(42)
	v_add_f32_e32 v88, v3, v104
	v_pk_mul_f32 v[88:89], v[86:87], v[88:89] op_sel:[1,0] op_sel_hi:[0,0]
	v_pk_fma_f32 v[92:93], v[86:87], v[90:91], v[88:89] neg_lo:[0,0,1] neg_hi:[0,0,1]
	v_pk_fma_f32 v[88:89], v[86:87], v[90:91], v[88:89] op_sel_hi:[1,0,1]
	s_nop 0
	v_mov_b32_e32 v93, v89
	s_waitcnt vmcnt(40)
	v_add_f32_e32 v88, v92, v42
	v_add_f32_e32 v89, v93, v43
	s_nop 0
	v_mul_f32_e32 v90, v86, v88
	v_mul_f32_e32 v91, v87, v89
	v_pk_mul_f32 v[88:89], v[86:87], v[88:89] op_sel:[0,1] op_sel_hi:[1,0]
	v_sub_f32_e32 v3, v90, v91
	s_waitcnt vmcnt(39)
	v_add_f32_e32 v90, v3, v103
	v_add_f32_e32 v3, v88, v89
	s_waitcnt vmcnt(38)
	v_add_f32_e32 v88, v3, v102
	v_pk_mul_f32 v[88:89], v[86:87], v[88:89] op_sel:[1,0] op_sel_hi:[0,0]
	v_pk_fma_f32 v[92:93], v[86:87], v[90:91], v[88:89] neg_lo:[0,0,1] neg_hi:[0,0,1]
	v_pk_fma_f32 v[88:89], v[86:87], v[90:91], v[88:89] op_sel_hi:[1,0,1]
	s_nop 0
	v_mov_b32_e32 v93, v89
	s_waitcnt vmcnt(36)
	v_add_f32_e32 v88, v92, v40
	v_add_f32_e32 v89, v93, v41
	s_nop 0
	v_mul_f32_e32 v90, v86, v88
	v_mul_f32_e32 v91, v87, v89
	v_pk_mul_f32 v[88:89], v[86:87], v[88:89] op_sel:[0,1] op_sel_hi:[1,0]
	v_sub_f32_e32 v3, v90, v91
	s_waitcnt vmcnt(35)
	v_add_f32_e32 v90, v3, v101
	v_add_f32_e32 v3, v88, v89
	s_waitcnt vmcnt(34)
	v_add_f32_e32 v88, v3, v100
	v_pk_mul_f32 v[88:89], v[86:87], v[88:89] op_sel:[1,0] op_sel_hi:[0,0]
	v_pk_fma_f32 v[92:93], v[86:87], v[90:91], v[88:89] neg_lo:[0,0,1] neg_hi:[0,0,1]
	v_pk_fma_f32 v[88:89], v[86:87], v[90:91], v[88:89] op_sel_hi:[1,0,1]
	s_nop 0
	v_mov_b32_e32 v93, v89
	s_waitcnt vmcnt(32)
	v_add_f32_e32 v88, v92, v38
	v_add_f32_e32 v89, v93, v39
	s_nop 0
	v_mul_f32_e32 v90, v86, v88
	v_mul_f32_e32 v91, v87, v89
	v_pk_mul_f32 v[88:89], v[86:87], v[88:89] op_sel:[0,1] op_sel_hi:[1,0]
	v_sub_f32_e32 v3, v90, v91
	s_waitcnt vmcnt(31)
	v_add_f32_e32 v90, v3, v99
	v_add_f32_e32 v3, v88, v89
	s_waitcnt vmcnt(30)
	v_add_f32_e32 v88, v3, v98
	v_mul_f32_e32 v89, v87, v88
	v_mul_f32_e32 v88, v86, v88
	s_nop 0
	v_pk_fma_f32 v[92:93], v[86:87], v[90:91], v[88:89] op_sel:[1,0,0] op_sel_hi:[0,1,1]
	v_pk_fma_f32 v[88:89], v[86:87], v[90:91], v[88:89] op_sel:[1,0,0] op_sel_hi:[0,0,1] neg_lo:[0,0,1] neg_hi:[0,0,1]
	v_mov_b32_e32 v93, v89
	s_waitcnt vmcnt(28)
	v_add_f32_e32 v88, v92, v36
	v_add_f32_e32 v89, v93, v37
	s_nop 0
	v_pk_mul_f32 v[90:91], v[86:87], v[88:89] op_sel:[1,0]
	s_nop 0
	v_pk_fma_f32 v[92:93], v[86:87], v[88:89], v[90:91] op_sel:[0,0,1] op_sel_hi:[1,1,0]
	v_pk_fma_f32 v[88:89], v[86:87], v[88:89], v[90:91] op_sel:[0,0,1] op_sel_hi:[0,1,0] neg_lo:[0,0,1] neg_hi:[0,0,1]
	v_mov_b32_e32 v93, v89
	s_waitcnt vmcnt(26)
	v_add_f32_e32 v88, v92, v34
	v_add_f32_e32 v89, v93, v35
	s_nop 0
	v_pk_mul_f32 v[90:91], v[86:87], v[88:89] op_sel:[1,0]
	s_nop 0
	v_pk_fma_f32 v[92:93], v[86:87], v[88:89], v[90:91] op_sel:[0,0,1] op_sel_hi:[1,1,0]
	v_pk_fma_f32 v[88:89], v[86:87], v[88:89], v[90:91] op_sel:[0,0,1] op_sel_hi:[0,1,0] neg_lo:[0,0,1] neg_hi:[0,0,1]
	v_mov_b32_e32 v93, v89
	s_waitcnt vmcnt(24)
	v_add_f32_e32 v88, v92, v32
	v_add_f32_e32 v89, v93, v33
	s_nop 0
	v_pk_mul_f32 v[90:91], v[86:87], v[88:89] op_sel:[1,0]
	s_nop 0
	v_pk_fma_f32 v[92:93], v[86:87], v[88:89], v[90:91] op_sel:[0,0,1] op_sel_hi:[1,1,0]
	v_pk_fma_f32 v[88:89], v[86:87], v[88:89], v[90:91] op_sel:[0,0,1] op_sel_hi:[0,1,0] neg_lo:[0,0,1] neg_hi:[0,0,1]
	v_mov_b32_e32 v93, v89
	s_waitcnt vmcnt(22)
	v_add_f32_e32 v88, v92, v30
	v_add_f32_e32 v89, v93, v31
	s_nop 0
	v_mul_f32_e32 v90, v87, v88
	v_mul_f32_e32 v92, v86, v88
	v_pk_fma_f32 v[90:91], v[86:87], v[88:89], v[90:91] op_sel:[0,1,0] op_sel_hi:[1,0,0] neg_lo:[0,0,1] neg_hi:[0,0,1]
	v_pk_fma_f32 v[88:89], v[86:87], v[88:89], v[92:93] op_sel_hi:[1,1,0]
	s_nop 0
	v_mov_b32_e32 v91, v89
	s_waitcnt vmcnt(20)
	v_add_f32_e32 v88, v90, v28
	v_add_f32_e32 v89, v91, v29
	s_nop 0
	v_pk_mul_f32 v[90:91], v[86:87], v[88:89] op_sel:[1,0]
	s_nop 0
	v_pk_fma_f32 v[92:93], v[86:87], v[88:89], v[90:91] op_sel:[0,0,1] op_sel_hi:[1,1,0] neg_lo:[0,0,1] neg_hi:[0,0,1]
	v_pk_fma_f32 v[88:89], v[86:87], v[88:89], v[90:91] op_sel:[0,0,1] op_sel_hi:[0,1,0]
	v_mov_b32_e32 v93, v89
	s_waitcnt vmcnt(18)
	v_add_f32_e32 v88, v92, v26
	v_add_f32_e32 v89, v93, v27
	s_nop 0
	v_pk_mul_f32 v[90:91], v[86:87], v[88:89] op_sel:[1,0]
	s_nop 0
	v_pk_fma_f32 v[92:93], v[86:87], v[88:89], v[90:91] op_sel:[0,0,1] op_sel_hi:[1,1,0] neg_lo:[0,0,1] neg_hi:[0,0,1]
	v_pk_fma_f32 v[88:89], v[86:87], v[88:89], v[90:91] op_sel:[0,0,1] op_sel_hi:[0,1,0]
	v_mov_b32_e32 v93, v89
	s_waitcnt vmcnt(16)
; #define LAS __attribute__((address_space(3)))
; __global__ void __launch_bounds__(NWAVES * 64, 2) mega_fwd(Args args) {
;     ...
;             for (int q = 0; q < 64; ++q) { const float nr = ar * sr - ai * si + er[q], ni = ar * si + ai * sr + ei[q]; sr = nr; si = ni; }
;             LAS float* segE = (LAS float*)lds;
;             segE[(seg * 64 + p) * 2] = sr; segE[(seg * 64 + p) * 2 + 1] = si;
;             float br = ar, bi = ai;
; #pragma unroll
;             for (int q = 0; q < 6; ++q) { const float nr = br * br - bi * bi, ni = 2.0f * br * bi; br = nr; bi = ni; }
;             __syncthreads();
;             sr = 0.f; si = 0.f;
;             for (int v = 0; v < seg; ++v) { const float e0 = segE[(v * 64 + p) * 2], e1 = segE[(v * 64 + p) * 2 + 1]; const float nr = br * sr - bi * si + e0, ni = br * si + bi * sr + e1; sr = nr; si = ni; }
;             if (seg == 0) { bf16* z0 = Ab + (size_t)(dir ? 511 : 0) * 512; z0[0] = 0; z0[64] = 0; }
	v_add_f32_e32 v88, v92, v24
	v_add_f32_e32 v89, v93, v25
	s_nop 0
	v_pk_mul_f32 v[90:91], v[86:87], v[88:89] op_sel:[1,0]
	s_nop 0
	v_pk_fma_f32 v[92:93], v[86:87], v[88:89], v[90:91] op_sel:[0,0,1] op_sel_hi:[1,1,0] neg_lo:[0,0,1] neg_hi:[0,0,1]
	v_pk_fma_f32 v[88:89], v[86:87], v[88:89], v[90:91] op_sel:[0,0,1] op_sel_hi:[0,1,0]
	v_mov_b32_e32 v93, v89
	s_waitcnt vmcnt(14)
	v_add_f32_e32 v88, v92, v22
	v_add_f32_e32 v89, v93, v23
	s_nop 0
	v_pk_mul_f32 v[90:91], v[86:87], v[88:89] op_sel:[1,0]
	s_nop 0
	v_pk_fma_f32 v[92:93], v[86:87], v[88:89], v[90:91] op_sel:[0,0,1] op_sel_hi:[1,1,0] neg_lo:[0,0,1] neg_hi:[0,0,1]
	v_pk_fma_f32 v[88:89], v[86:87], v[88:89], v[90:91] op_sel:[0,0,1] op_sel_hi:[0,1,0]
	v_mov_b32_e32 v93, v89
	s_waitcnt vmcnt(12)
	v_add_f32_e32 v88, v92, v20
	v_add_f32_e32 v89, v93, v21
	s_nop 0
	v_pk_mul_f32 v[90:91], v[86:87], v[88:89] op_sel:[1,0]
	s_nop 0
	v_pk_fma_f32 v[92:93], v[86:87], v[88:89], v[90:91] op_sel:[0,0,1] op_sel_hi:[1,1,0] neg_lo:[0,0,1] neg_hi:[0,0,1]
	v_pk_fma_f32 v[88:89], v[86:87], v[88:89], v[90:91] op_sel:[0,0,1] op_sel_hi:[0,1,0]
	v_mov_b32_e32 v93, v89
	s_waitcnt vmcnt(10)
	v_add_f32_e32 v88, v92, v18
	v_add_f32_e32 v89, v93, v19
	s_nop 0
	v_pk_mul_f32 v[90:91], v[86:87], v[88:89] op_sel:[1,0]
	s_nop 0
	v_pk_fma_f32 v[92:93], v[86:87], v[88:89], v[90:91] op_sel:[0,0,1] op_sel_hi:[1,1,0] neg_lo:[0,0,1] neg_hi:[0,0,1]
	v_pk_fma_f32 v[88:89], v[86:87], v[88:89], v[90:91] op_sel:[0,0,1] op_sel_hi:[0,1,0]
	v_mov_b32_e32 v93, v89
	s_waitcnt vmcnt(8)
	v_add_f32_e32 v88, v92, v16
	v_add_f32_e32 v89, v93, v17
	s_nop 0
	v_pk_mul_f32 v[90:91], v[86:87], v[88:89] op_sel:[1,0]
	s_nop 0
	v_pk_fma_f32 v[92:93], v[86:87], v[88:89], v[90:91] op_sel:[0,0,1] op_sel_hi:[1,1,0] neg_lo:[0,0,1] neg_hi:[0,0,1]
	v_pk_fma_f32 v[88:89], v[86:87], v[88:89], v[90:91] op_sel:[0,0,1] op_sel_hi:[0,1,0]
	v_mov_b32_e32 v93, v89
	s_waitcnt vmcnt(6)
	v_add_f32_e32 v88, v92, v14
	v_add_f32_e32 v89, v93, v15
	s_nop 0
	v_pk_mul_f32 v[90:91], v[86:87], v[88:89] op_sel:[1,0]
	s_nop 0
	v_pk_fma_f32 v[92:93], v[86:87], v[88:89], v[90:91] op_sel:[0,0,1] op_sel_hi:[1,1,0] neg_lo:[0,0,1] neg_hi:[0,0,1]
	v_pk_fma_f32 v[88:89], v[86:87], v[88:89], v[90:91] op_sel:[0,0,1] op_sel_hi:[0,1,0]
	v_mov_b32_e32 v93, v89
	s_waitcnt vmcnt(4)
	v_add_f32_e32 v88, v92, v12
	v_add_f32_e32 v89, v93, v13
	s_nop 0
	v_pk_mul_f32 v[90:91], v[86:87], v[88:89] op_sel:[1,0]
	s_nop 0
	v_pk_fma_f32 v[92:93], v[86:87], v[88:89], v[90:91] op_sel:[0,0,1] op_sel_hi:[1,1,0] neg_lo:[0,0,1] neg_hi:[0,0,1]
	v_pk_fma_f32 v[88:89], v[86:87], v[88:89], v[90:91] op_sel:[0,0,1] op_sel_hi:[0,1,0]
	v_mov_b32_e32 v93, v89
	s_waitcnt vmcnt(2)
	v_add_f32_e32 v88, v92, v10
	v_add_f32_e32 v89, v93, v11
	s_nop 0
	v_pk_mul_f32 v[90:91], v[86:87], v[88:89] op_sel:[1,0]
	s_nop 0
	v_pk_fma_f32 v[92:93], v[86:87], v[88:89], v[90:91] op_sel:[0,0,1] op_sel_hi:[1,1,0] neg_lo:[0,0,1] neg_hi:[0,0,1]
	v_pk_fma_f32 v[88:89], v[86:87], v[88:89], v[90:91] op_sel:[0,0,1] op_sel_hi:[0,1,0]
	v_mov_b32_e32 v93, v89
	s_waitcnt vmcnt(0)
	v_add_f32_e32 v88, v92, v8
	v_add_f32_e32 v89, v93, v9
	v_mov_b32_e32 v93, 0
	v_mov_b32_e32 v92, 0
	ds_write_b64 v97, v[88:89]
	s_waitcnt lgkmcnt(0)
	s_barrier
	s_cbranch_vccnz .LBB0_688
	v_mul_f32_e32 v88, v86, v86
	v_mul_f32_e32 v89, v87, v87
	v_readlane_b32 vcc_lo, v254, 45
	v_sub_f32_e32 v3, v88, v89
	v_add_f32_e32 v88, v86, v86
	v_mul_f32_e32 v88, v87, v88
	v_mul_f32_e32 v89, v3, v3
	v_add_f32_e32 v3, v3, v3
	v_mul_f32_e32 v3, v88, v3
	v_fma_f32 v89, -v88, v88, v89
	v_mul_f32_e32 v88, v3, v3
	v_fma_f32 v88, v89, v89, -v88
	v_add_f32_e32 v89, v89, v89
	v_mul_f32_e32 v3, v3, v89
	v_mul_f32_e32 v89, v3, v3
	v_fma_f32 v89, v88, v88, -v89
	v_add_f32_e32 v88, v88, v88
	v_mul_f32_e32 v3, v3, v88
	v_mul_f32_e32 v88, v3, v3
	v_fma_f32 v90, v89, v89, -v88
	v_add_f32_e32 v88, v89, v89
	v_mul_f32_e32 v3, v3, v88
	v_mul_f32_e32 v88, v3, v3
	v_add_f32_e32 v89, v90, v90
	v_readlane_b32 vcc_hi, v254, 46
	v_fma_f32 v88, v90, v90, -v88
	s_andn2_b64 vcc, exec, vcc
	v_mul_f32_e32 v90, v3, v89
	s_cbranch_vccnz .LBB0_684
	v_mov_b32_e32 v92, 0
	v_mov_b32_e32 v89, v88
	v_mov_b32_e32 v91, v90
	s_mov_b32 s1, 0
	v_mov_b32_e32 v3, v95
	v_mov_b32_e32 v93, v92
; __global__ void __launch_bounds__(NWAVES * 64, 2) mega_fwd(Args args) {
;     ...
;             for (int v = 0; v < seg; ++v) { const float e0 = segE[(v * 64 + p) * 2], e1 = segE[(v * 64 + p) * 2 + 1]; const float nr = br * sr - bi * si + e0, ni = br * si + bi * sr + e1; sr = nr; si = ni; }
.LBB0_682:
	ds_read2st64_b64 v[148:151], v3 offset1:1
	v_pk_mul_f32 v[152:153], v[90:91], v[92:93] op_sel:[0,1] op_sel_hi:[1,0]
	s_add_i32 s1, s1, 8
	v_pk_fma_f32 v[154:155], v[88:89], v[92:93], v[152:153]
	v_pk_fma_f32 v[92:93], v[88:89], v[92:93], v[152:153] neg_lo:[0,0,1] neg_hi:[0,0,1]
	s_cmp_eq_u32 s33, s1
	v_mov_b32_e32 v93, v155
	s_waitcnt lgkmcnt(0)
	v_add_f32_e32 v92, v92, v148
	v_add_f32_e32 v93, v93, v149
	s_nop 0
	v_pk_mul_f32 v[148:149], v[90:91], v[92:93] op_sel:[0,1] op_sel_hi:[1,0]
	s_nop 0
	v_pk_fma_f32 v[152:153], v[88:89], v[92:93], v[148:149]
	v_pk_fma_f32 v[92:93], v[88:89], v[92:93], v[148:149] neg_lo:[0,0,1] neg_hi:[0,0,1]
	s_nop 0
	v_mov_b32_e32 v93, v153
	v_add_f32_e32 v92, v92, v150
	v_add_f32_e32 v93, v93, v151
	ds_read2st64_b64 v[148:151], v3 offset0:2 offset1:3
	v_pk_mul_f32 v[152:153], v[90:91], v[92:93] op_sel:[0,1] op_sel_hi:[1,0]
	s_nop 0
	v_pk_fma_f32 v[154:155], v[88:89], v[92:93], v[152:153]
	v_pk_fma_f32 v[92:93], v[88:89], v[92:93], v[152:153] neg_lo:[0,0,1] neg_hi:[0,0,1]
	s_nop 0
	v_mov_b32_e32 v93, v155
	s_waitcnt lgkmcnt(0)
	v_add_f32_e32 v92, v92, v148
	v_add_f32_e32 v93, v93, v149
	s_nop 0
	v_pk_mul_f32 v[148:149], v[90:91], v[92:93] op_sel:[0,1] op_sel_hi:[1,0]
	s_nop 0
	v_pk_fma_f32 v[152:153], v[88:89], v[92:93], v[148:149]
	v_pk_fma_f32 v[92:93], v[88:89], v[92:93], v[148:149] neg_lo:[0,0,1] neg_hi:[0,0,1]
	s_nop 0
	v_mov_b32_e32 v93, v153
	v_add_f32_e32 v92, v92, v150
	v_add_f32_e32 v93, v93, v151
	ds_read2st64_b64 v[148:151], v3 offset0:4 offset1:5
	v_pk_mul_f32 v[152:153], v[90:91], v[92:93] op_sel:[0,1] op_sel_hi:[1,0]
	s_nop 0
	v_pk_fma_f32 v[154:155], v[88:89], v[92:93], v[152:153]
	v_pk_fma_f32 v[92:93], v[88:89], v[92:93], v[152:153] neg_lo:[0,0,1] neg_hi:[0,0,1]
	s_nop 0
	v_mov_b32_e32 v93, v155
	s_waitcnt lgkmcnt(0)
	v_add_f32_e32 v92, v92, v148
	v_add_f32_e32 v93, v93, v149
	s_nop 0
	v_pk_mul_f32 v[148:149], v[90:91], v[92:93] op_sel:[0,1] op_sel_hi:[1,0]
	s_nop 0
	v_pk_fma_f32 v[152:153], v[88:89], v[92:93], v[148:149]
	v_pk_fma_f32 v[92:93], v[88:89], v[92:93], v[148:149] neg_lo:[0,0,1] neg_hi:[0,0,1]
	s_nop 0
	v_mov_b32_e32 v93, v153
	v_add_f32_e32 v92, v92, v150
	v_add_f32_e32 v93, v93, v151
	ds_read2st64_b64 v[148:151], v3 offset0:6 offset1:7
	v_pk_mul_f32 v[152:153], v[90:91], v[92:93] op_sel:[0,1] op_sel_hi:[1,0]
	v_add_u32_e32 v3, 0x1000, v3
	v_pk_fma_f32 v[154:155], v[88:89], v[92:93], v[152:153]
	v_pk_fma_f32 v[92:93], v[88:89], v[92:93], v[152:153] neg_lo:[0,0,1] neg_hi:[0,0,1]
	s_nop 0
	v_mov_b32_e32 v93, v155
	s_waitcnt lgkmcnt(0)
	v_add_f32_e32 v92, v92, v148
	v_add_f32_e32 v93, v93, v149
	s_nop 0
	v_pk_mul_f32 v[148:149], v[90:91], v[92:93] op_sel:[0,1] op_sel_hi:[1,0]
	s_nop 0
	v_pk_fma_f32 v[152:153], v[88:89], v[92:93], v[148:149]
	v_pk_fma_f32 v[92:93], v[88:89], v[92:93], v[148:149] neg_lo:[0,0,1] neg_hi:[0,0,1]
	s_nop 0
	v_mov_b32_e32 v93, v153
	v_add_f32_e32 v92, v92, v150
	v_add_f32_e32 v93, v93, v151
	s_cbranch_scc0 .LBB0_682
	s_mov_b32 s1, s33
	s_branch .LBB0_685

; __global__ void __launch_bounds__(NWAVES * 64, 2) mega_fwd(Args args) {
;     ...
;             for (int v = 0; v < seg; ++v) { const float e0 = segE[(v * 64 + p) * 2], e1 = segE[(v * 64 + p) * 2 + 1]; const float nr = br * sr - bi * si + e0, ni = br * si + bi * sr + e1; sr = nr; si = ni; }
.LBB0_687:
	ds_read_b64 v[150:151], v3
	v_pk_mul_f32 v[148:149], v[90:91], v[92:93] op_sel:[0,1] op_sel_hi:[1,0]
	s_add_i32 s1, s1, -1
	v_pk_fma_f32 v[152:153], v[88:89], v[92:93], v[148:149]
	v_pk_fma_f32 v[92:93], v[88:89], v[92:93], v[148:149] neg_lo:[0,0,1] neg_hi:[0,0,1]
	v_add_u32_e32 v3, 0x200, v3
	v_mov_b32_e32 v93, v153
	s_cmp_lg_u32 s1, 0
	s_waitcnt lgkmcnt(0)
	v_add_f32_e32 v92, v92, v150
	v_add_f32_e32 v93, v93, v151
	s_cbranch_scc1 .LBB0_687

; __device__ __forceinline__ unsigned f2bf(float f) { unsigned u = __builtin_bit_cast(unsigned, f); return (u + 0x7fffu + ((u >> 16) & 1u)) >> 16; }
; __global__ void __launch_bounds__(NWAVES * 64, 2) mega_fwd(Args args) {
;     ...
;             for (int q = 0; q < 64; ++q) { const int sidx = seg * 64 + q, c = dir ? 511 - sidx : sidx; const float nr = ar * sr - ai * si + er[q], ni = ar * si + ai * sr + ei[q]; sr = nr; si = ni;
;                 const int cd = dir ? c - 1 : c + 1;
;                 if (cd >= 0 && cd < 512) { Ab[(size_t)cd * 512] = (bf16)f2bf(sr); Ab[(size_t)cd * 512 + 64] = (bf16)f2bf(si); } }
.LBB0_690:
	s_and_b64 s[40:41], s[40:41], exec
	v_mul_f32_e32 v90, v86, v92
	v_mul_f32_e32 v91, v87, v93
	s_cselect_b32 s1, 1, -1
	v_sub_f32_e32 v3, v90, v91
	v_mul_f32_e32 v90, v86, v93
	v_fmac_f32_e32 v90, v87, v92
	s_add_i32 s3, s64, s1
	v_add_f32_e32 v3, v3, v147
	s_cmpk_gt_u32 s3, 0x1ff
	v_add_f32_e32 v90, v90, v145
	s_cbranch_scc1 .LBB0_692
	s_lshl_b32 s10, s3, 10
	v_cvt_pk_bf16_f32 v91, v3, v90
	v_lshl_add_u64 v[92:93], v[88:89], 0, s[10:11]
	global_store_short v[92:93], v91, off offset:512
	global_store_short_d16_hi v[92:93], v91, off offset:640
